# ctx operand cache prefetch moved under the last in-proj epilogue (latency hidden)
# speedup vs baseline: 1.0153x; 1.0015x over previous
; #define PG8_STAGE(bufoff, gbase, voff) do { _Pragma("unroll") for (int _i = 0; _i < 2; ++_i) \
;         __builtin_amdgcn_global_load_lds((const unsigned*)((const char*)(gbase) + (voff)[_i]), (LAS unsigned*)(lds + (bufoff) + ldsw + _i * 8192), 16, 0, 0); } while (0)
; #define PG8_LDA(dst, b, h) do { _Pragma("unroll") for (int m = 0; m < 4; ++m) _Pragma("unroll") for (int k = 0; k < 2; ++k) dst[m][k] = *(const LAS bf16x8*)(lds + PG8_SA(b, h) + aoff + m * 2048 + k * 1024); } while (0)
; #define PG8_LDB(dst, b, h) do { _Pragma("unroll") for (int n = 0; n < 2; ++n) _Pragma("unroll") for (int k = 0; k < 2; ++k) dst[n][k] = *(const LAS bf16x8*)(lds + PG8_SB(b, h) + boff + n * 2048 + k * 1024); } while (0)
; #define PG8_MMA(ai, bj, At, Bt) do { __builtin_amdgcn_s_setprio(1); _Pragma("unroll") for (int m = 0; m < 4; ++m) _Pragma("unroll") for (int n = 0; n < 2; ++n) _Pragma("unroll") for (int k = 0; k < 2; ++k) \
;         acc[ai][bj][m][n] = __builtin_amdgcn_mfma_f32_16x16x32_bf16(Bt[n][k], At[m][k], acc[ai][bj][m][n], 0, 0, 0); __builtin_amdgcn_s_setprio(0); } while (0)
; #define PG8_WAIT_V(n) asm volatile("s_waitcnt vmcnt(" #n ")" ::: "memory")
; #define PG8_WAIT_L(n) asm volatile("s_waitcnt lgkmcnt(" #n ")" ::: "memory")
; template <class Epi, class Sched>
; __device__ __forceinline__ void gemm_phase(LAS unsigned char* lds, const Gemm g, const Sched& S, const Epi& E) {
;     ...
;         for (int t = 0; t < nt; t += 2) {
;             const bool last = (t == nt - 2);
;             const char* a1 = cA + (size_t)(t >> 1) * g.pairstep + kstep;
;             const char* a2 = last ? nA : cA + (size_t)((t >> 1) + 1) * g.pairstep; const char* b2 = last ? nB : cB + (size_t)(t + 2) * kstep;
;             const char* a3 = a2 + kstep; const char* b3 = b2 + kstep;
;             PG8_LDB(B0, 0, 0); PG8_SCHED; PG8_LDA(At, 0, 0); PG8_STAGE(PG8_SA(1, 1), a1 + hstepA, voffA);
;             PG8_WAIT_L(8); PG8_BAR; PG8_WAIT_L(0); PG8_MMA(0, 0, At, B0); PG8_BAR; PG8_SCHED;
;             PG8_LDB(B1, 0, 1); PG8_STAGE(PG8_SB(0, 0), b2, voffB);
;             PG8_BAR; PG8_WAIT_L(0); PG8_MMA(0, 1, At, B1); PG8_BAR;
;             PG8_LDA(At, 0, 1); PG8_STAGE(PG8_SA(0, 0), a2, voffA);
;             PG8_BAR; PG8_WAIT_L(0); PG8_MMA(1, 0, At, B0); PG8_BAR; PG8_SCHED;
;             PG8_STAGE(PG8_SB(0, 1), b2 + hstepB, voffB);
;             PG8_WAIT_V(6); PG8_BAR; PG8_MMA(1, 1, At, B1); PG8_BAR;
.LBB0_140:
	s_add_u32 s49, s70, 0xfffc0080
	s_addc_u32 s51, s71, -1
	s_add_i32 vcc_lo, 0, 0x10000
	v_add_u32_e32 v129, vcc_lo, v164
	ds_read_b128 v[150:153], v129
	ds_read_b128 v[154:157], v129 offset:1024
	ds_read_b128 v[168:171], v129 offset:2048
	ds_read_b128 v[172:175], v129 offset:3072
	s_cmp_eq_u32 s29, 12
	s_cselect_b32 s75, s11, s51
	s_cselect_b32 s74, s14, s49
	s_cselect_b32 s73, s25, s28
	s_cselect_b32 s72, s26, s27
	v_lshl_add_u64 v[158:159], s[70:71], 0, v[144:145]
	s_add_i32 m0, s96, 0xc000
	ds_read_b128 v[176:179], v165
	ds_read_b128 v[180:183], v165 offset:1024
	ds_read_b128 v[184:187], v165 offset:2048
	ds_read_b128 v[188:191], v165 offset:3072
	ds_read_b128 v[192:195], v165 offset:4096
	ds_read_b128 v[196:199], v165 offset:5120
	ds_read_b128 v[200:203], v165 offset:6144
	ds_read_b128 v[204:207], v165 offset:7168
	global_load_lds_dwordx4 v[158:159], off
	v_lshl_add_u64 v[158:159], s[70:71], 0, v[146:147]
	s_add_i32 m0, s96, 0xe000
	s_nop 0
	global_load_lds_dwordx4 v[158:159], off
	s_waitcnt lgkmcnt(8)
	s_barrier
	s_waitcnt lgkmcnt(0)
	s_setprio 1
	s_waitcnt lgkmcnt(0)
	v_mfma_f32_16x16x32_bf16 v[124:127], v[150:153], v[176:179], v[124:127]
	v_mfma_f32_16x16x32_bf16 v[120:123], v[168:171], v[176:179], v[120:123]
	v_mfma_f32_16x16x32_bf16 v[112:115], v[150:153], v[184:187], v[112:115]
	v_mfma_f32_16x16x32_bf16 v[104:107], v[168:171], v[184:187], v[104:107]
	v_mfma_f32_16x16x32_bf16 v[96:99], v[150:153], v[192:195], v[96:99]
	v_mfma_f32_16x16x32_bf16 v[88:91], v[168:171], v[192:195], v[88:91]
	v_mfma_f32_16x16x32_bf16 v[80:83], v[150:153], v[200:203], v[80:83]
	v_mfma_f32_16x16x32_bf16 v[72:75], v[168:171], v[200:203], v[72:75]
	v_mfma_f32_16x16x32_bf16 v[124:127], v[154:157], v[180:183], v[124:127]
	v_mfma_f32_16x16x32_bf16 v[120:123], v[172:175], v[180:183], v[120:123]
	v_mfma_f32_16x16x32_bf16 v[112:115], v[154:157], v[188:191], v[112:115]
	v_mfma_f32_16x16x32_bf16 v[104:107], v[172:175], v[188:191], v[104:107]
	v_mfma_f32_16x16x32_bf16 v[96:99], v[154:157], v[196:199], v[96:99]
	v_mfma_f32_16x16x32_bf16 v[88:91], v[172:175], v[196:199], v[88:91]
	v_mfma_f32_16x16x32_bf16 v[80:83], v[154:157], v[204:207], v[80:83]
	v_mfma_f32_16x16x32_bf16 v[72:75], v[172:175], v[204:207], v[72:75]
	s_setprio 0
	s_barrier
	s_add_i32 s49, 0, 0x14000
	s_add_i32 s51, vcc_lo, s95
	v_add_u32_e32 v129, s49, v164
	v_lshl_add_u64 v[158:159], s[72:73], 0, v[138:139]
	s_mov_b32 m0, s51
	ds_read_b128 v[208:211], v129
	ds_read_b128 v[212:215], v129 offset:1024
	ds_read_b128 v[216:219], v129 offset:2048
	ds_read_b128 v[220:223], v129 offset:3072
	global_load_lds_dwordx4 v[158:159], off
	v_lshl_add_u64 v[224:225], s[72:73], 0, v[134:135]
	s_add_i32 m0, s51, 0x2000
	s_nop 0
	global_load_lds_dwordx4 v[224:225], off
	s_barrier
	s_waitcnt lgkmcnt(0)
	s_setprio 1
	s_waitcnt lgkmcnt(0)
	v_mfma_f32_16x16x32_bf16 v[116:119], v[208:211], v[176:179], v[116:119]
	v_mfma_f32_16x16x32_bf16 v[108:111], v[216:219], v[176:179], v[108:111]
	v_mfma_f32_16x16x32_bf16 v[100:103], v[208:211], v[184:187], v[100:103]
	v_mfma_f32_16x16x32_bf16 v[92:95], v[216:219], v[184:187], v[92:95]
	v_mfma_f32_16x16x32_bf16 v[84:87], v[208:211], v[192:195], v[84:87]
	v_mfma_f32_16x16x32_bf16 v[76:79], v[216:219], v[192:195], v[76:79]
	v_mfma_f32_16x16x32_bf16 v[68:71], v[208:211], v[200:203], v[68:71]
	v_mfma_f32_16x16x32_bf16 v[64:67], v[216:219], v[200:203], v[64:67]
	v_mfma_f32_16x16x32_bf16 v[116:119], v[212:215], v[180:183], v[116:119]
	v_mfma_f32_16x16x32_bf16 v[108:111], v[220:223], v[180:183], v[108:111]
	v_mfma_f32_16x16x32_bf16 v[100:103], v[212:215], v[188:191], v[100:103]
	v_mfma_f32_16x16x32_bf16 v[92:95], v[220:223], v[188:191], v[92:95]
	v_mfma_f32_16x16x32_bf16 v[84:87], v[212:215], v[196:199], v[84:87]
	v_mfma_f32_16x16x32_bf16 v[76:79], v[220:223], v[196:199], v[76:79]
	v_mfma_f32_16x16x32_bf16 v[68:71], v[212:215], v[204:207], v[68:71]
	v_mfma_f32_16x16x32_bf16 v[64:67], v[220:223], v[204:207], v[64:67]
	s_setprio 0
	s_mov_b32 m0, s96
	v_lshl_add_u64 v[226:227], s[74:75], 0, v[140:141]
	s_barrier
	ds_read_b128 v[176:179], v165 offset:16384
	ds_read_b128 v[180:183], v165 offset:17408
	ds_read_b128 v[184:187], v165 offset:18432
	ds_read_b128 v[188:191], v165 offset:19456
	ds_read_b128 v[192:195], v165 offset:20480
	ds_read_b128 v[196:199], v165 offset:21504
	ds_read_b128 v[200:203], v165 offset:22528
	ds_read_b128 v[204:207], v165 offset:23552
	global_load_lds_dwordx4 v[226:227], off
	v_lshl_add_u64 v[228:229], s[74:75], 0, v[136:137]
	s_mov_b32 m0, s97
	s_nop 0
	global_load_lds_dwordx4 v[228:229], off
	s_barrier
	s_waitcnt lgkmcnt(0)
	s_setprio 1
	s_waitcnt lgkmcnt(0)
	v_mfma_f32_16x16x32_bf16 v[60:63], v[150:153], v[176:179], v[60:63]
	v_mfma_f32_16x16x32_bf16 v[56:59], v[168:171], v[176:179], v[56:59]
	v_mfma_f32_16x16x32_bf16 v[48:51], v[150:153], v[184:187], v[48:51]
	v_mfma_f32_16x16x32_bf16 v[40:43], v[168:171], v[184:187], v[40:43]
	v_mfma_f32_16x16x32_bf16 v[36:39], v[150:153], v[192:195], v[36:39]
	v_mfma_f32_16x16x32_bf16 v[28:31], v[168:171], v[192:195], v[28:31]
	v_mfma_f32_16x16x32_bf16 v[20:23], v[150:153], v[200:203], v[20:23]
	v_mfma_f32_16x16x32_bf16 v[12:15], v[168:171], v[200:203], v[12:15]
	v_mfma_f32_16x16x32_bf16 v[60:63], v[154:157], v[180:183], v[60:63]
	v_mfma_f32_16x16x32_bf16 v[56:59], v[172:175], v[180:183], v[56:59]
	v_mfma_f32_16x16x32_bf16 v[48:51], v[154:157], v[188:191], v[48:51]
	v_mfma_f32_16x16x32_bf16 v[40:43], v[172:175], v[188:191], v[40:43]
	v_mfma_f32_16x16x32_bf16 v[36:39], v[154:157], v[196:199], v[36:39]
	v_mfma_f32_16x16x32_bf16 v[28:31], v[172:175], v[196:199], v[28:31]
	v_mfma_f32_16x16x32_bf16 v[20:23], v[154:157], v[204:207], v[20:23]
	v_mfma_f32_16x16x32_bf16 v[12:15], v[172:175], v[204:207], v[12:15]
	s_setprio 0
	s_barrier
; #define PG8_STAGE(bufoff, gbase, voff) do { _Pragma("unroll") for (int _i = 0; _i < 2; ++_i) \
;         __builtin_amdgcn_global_load_lds((const unsigned*)((const char*)(gbase) + (voff)[_i]), (LAS unsigned*)(lds + (bufoff) + ldsw + _i * 8192), 16, 0, 0); } while (0)
; #define PG8_LDA(dst, b, h) do { _Pragma("unroll") for (int m = 0; m < 4; ++m) _Pragma("unroll") for (int k = 0; k < 2; ++k) dst[m][k] = *(const LAS bf16x8*)(lds + PG8_SA(b, h) + aoff + m * 2048 + k * 1024); } while (0)
; #define PG8_LDB(dst, b, h) do { _Pragma("unroll") for (int n = 0; n < 2; ++n) _Pragma("unroll") for (int k = 0; k < 2; ++k) dst[n][k] = *(const LAS bf16x8*)(lds + PG8_SB(b, h) + boff + n * 2048 + k * 1024); } while (0)
; #define PG8_MMA(ai, bj, At, Bt) do { __builtin_amdgcn_s_setprio(1); _Pragma("unroll") for (int m = 0; m < 4; ++m) _Pragma("unroll") for (int n = 0; n < 2; ++n) _Pragma("unroll") for (int k = 0; k < 2; ++k) \
;         acc[ai][bj][m][n] = __builtin_amdgcn_mfma_f32_16x16x32_bf16(Bt[n][k], At[m][k], acc[ai][bj][m][n], 0, 0, 0); __builtin_amdgcn_s_setprio(0); } while (0)
; #define PG8_WAIT_V(n) asm volatile("s_waitcnt vmcnt(" #n ")" ::: "memory")
; #define PG8_WAIT_L(n) asm volatile("s_waitcnt lgkmcnt(" #n ")" ::: "memory")
; #define PG8_BAR __builtin_amdgcn_s_barrier()
; #define PG8_SCHED __builtin_amdgcn_sched_barrier(0)
; template <class Epi, class Sched>
; __device__ __forceinline__ void gemm_phase(LAS unsigned char* lds, const Gemm g, const Sched& S, const Epi& E) {
;     ...
;             PG8_WAIT_V(6); PG8_BAR; PG8_MMA(1, 1, At, B1); PG8_BAR;
;             PG8_LDB(B0, 1, 0); PG8_SCHED; PG8_LDA(At, 1, 0); PG8_STAGE(PG8_SA(0, 1), a2 + hstepA, voffA);
;             PG8_WAIT_L(8); PG8_BAR; PG8_WAIT_L(0); PG8_MMA(0, 0, At, B0); PG8_BAR; PG8_SCHED;
;             PG8_LDB(B1, 1, 1); PG8_STAGE(PG8_SB(1, 0), b3, voffB);
;             PG8_BAR; PG8_WAIT_L(0); PG8_MMA(0, 1, At, B1); PG8_BAR;
;             PG8_LDA(At, 1, 1); PG8_STAGE(PG8_SA(1, 0), a3, voffA);
;             PG8_BAR; PG8_WAIT_L(0); PG8_MMA(1, 0, At, B0); PG8_BAR; PG8_SCHED;
	s_add_u32 vcc_lo, s72, 0x40000
	s_addc_u32 vcc_hi, s73, 0
	s_add_i32 s49, s49, s95
	v_lshl_add_u64 v[150:151], vcc, 0, v[138:139]
	s_mov_b32 m0, s49
	s_nop 0
	global_load_lds_dwordx4 v[150:151], off
	v_lshl_add_u64 v[150:151], vcc, 0, v[134:135]
	s_add_i32 m0, s49, 0x2000
	s_nop 0
	global_load_lds_dwordx4 v[150:151], off
	s_waitcnt vmcnt(6)
	s_barrier
	s_setprio 1
	v_mfma_f32_16x16x32_bf16 v[52:55], v[208:211], v[176:179], v[52:55]
	v_mfma_f32_16x16x32_bf16 v[44:47], v[216:219], v[176:179], v[44:47]
	v_mfma_f32_16x16x32_bf16 v[32:35], v[208:211], v[184:187], v[32:35]
	v_mfma_f32_16x16x32_bf16 v[24:27], v[216:219], v[184:187], v[24:27]
	v_mfma_f32_16x16x32_bf16 v[16:19], v[208:211], v[192:195], v[16:19]
	v_mfma_f32_16x16x32_bf16 v[8:11], v[216:219], v[192:195], v[8:11]
	v_mfma_f32_16x16x32_bf16 v[4:7], v[208:211], v[200:203], v[4:7]
	v_mfma_f32_16x16x32_bf16 v[0:3], v[216:219], v[200:203], v[0:3]
	v_mfma_f32_16x16x32_bf16 v[52:55], v[212:215], v[180:183], v[52:55]
	v_mfma_f32_16x16x32_bf16 v[44:47], v[220:223], v[180:183], v[44:47]
	v_mfma_f32_16x16x32_bf16 v[32:35], v[212:215], v[188:191], v[32:35]
	v_mfma_f32_16x16x32_bf16 v[24:27], v[220:223], v[188:191], v[24:27]
	v_mfma_f32_16x16x32_bf16 v[16:19], v[212:215], v[196:199], v[16:19]
	v_mfma_f32_16x16x32_bf16 v[8:11], v[220:223], v[196:199], v[8:11]
	v_mfma_f32_16x16x32_bf16 v[4:7], v[212:215], v[204:207], v[4:7]
	v_mfma_f32_16x16x32_bf16 v[0:3], v[220:223], v[204:207], v[0:3]
	s_setprio 0
	s_add_i32 s49, 0, 0x18000
	v_add_u32_e32 v129, s49, v164
	s_barrier
	ds_read_b128 v[150:153], v129
	ds_read_b128 v[154:157], v129 offset:1024
	ds_read_b128 v[168:171], v129 offset:2048
	ds_read_b128 v[172:175], v129 offset:3072
	s_add_u32 s74, s74, 0x40000
	s_addc_u32 s75, s75, 0
	s_mov_b32 m0, s33
	v_lshl_add_u64 v[208:209], s[74:75], 0, v[140:141]
	ds_read_b128 v[176:179], v165 offset:32768
	ds_read_b128 v[180:183], v165 offset:33792
	ds_read_b128 v[184:187], v165 offset:34816
	ds_read_b128 v[188:191], v165 offset:35840
	ds_read_b128 v[192:195], v165 offset:36864
	ds_read_b128 v[196:199], v165 offset:37888
	ds_read_b128 v[200:203], v165 offset:38912
	ds_read_b128 v[204:207], v165 offset:39936
	global_load_lds_dwordx4 v[208:209], off
	v_lshl_add_u64 v[208:209], s[74:75], 0, v[136:137]
	s_mov_b32 m0, s6
	s_nop 0
	global_load_lds_dwordx4 v[208:209], off
	s_waitcnt lgkmcnt(8)
	s_barrier
	s_waitcnt lgkmcnt(0)
	s_setprio 1
	s_waitcnt lgkmcnt(0)
	v_mfma_f32_16x16x32_bf16 v[124:127], v[150:153], v[176:179], v[124:127]
	v_mfma_f32_16x16x32_bf16 v[120:123], v[168:171], v[176:179], v[120:123]
	v_mfma_f32_16x16x32_bf16 v[112:115], v[150:153], v[184:187], v[112:115]
	v_mfma_f32_16x16x32_bf16 v[104:107], v[168:171], v[184:187], v[104:107]
	v_mfma_f32_16x16x32_bf16 v[96:99], v[150:153], v[192:195], v[96:99]
	v_mfma_f32_16x16x32_bf16 v[88:91], v[168:171], v[192:195], v[88:91]
	v_mfma_f32_16x16x32_bf16 v[80:83], v[150:153], v[200:203], v[80:83]
	v_mfma_f32_16x16x32_bf16 v[72:75], v[168:171], v[200:203], v[72:75]
	v_mfma_f32_16x16x32_bf16 v[124:127], v[154:157], v[180:183], v[124:127]
	v_mfma_f32_16x16x32_bf16 v[120:123], v[172:175], v[180:183], v[120:123]
	v_mfma_f32_16x16x32_bf16 v[112:115], v[154:157], v[188:191], v[112:115]
	v_mfma_f32_16x16x32_bf16 v[104:107], v[172:175], v[188:191], v[104:107]
	v_mfma_f32_16x16x32_bf16 v[96:99], v[154:157], v[196:199], v[96:99]
	v_mfma_f32_16x16x32_bf16 v[88:91], v[172:175], v[196:199], v[88:91]
	v_mfma_f32_16x16x32_bf16 v[80:83], v[154:157], v[204:207], v[80:83]
	v_mfma_f32_16x16x32_bf16 v[72:75], v[172:175], v[204:207], v[72:75]
	s_setprio 0
	s_barrier
	s_add_i32 s51, 0, 0x1c000
	s_add_i32 s49, s49, s95
	v_add_u32_e32 v129, s51, v164
	v_lshl_add_u64 v[158:159], v[158:159], 0, s[46:47]
	s_mov_b32 m0, s49
	ds_read_b128 v[208:211], v129
	ds_read_b128 v[212:215], v129 offset:1024
	ds_read_b128 v[216:219], v129 offset:2048
	ds_read_b128 v[220:223], v129 offset:3072
	global_load_lds_dwordx4 v[158:159], off
	v_lshl_add_u64 v[158:159], v[224:225], 0, s[46:47]
	s_add_i32 m0, s49, 0x2000
	s_nop 0
	global_load_lds_dwordx4 v[158:159], off
	s_barrier
	s_waitcnt lgkmcnt(0)
	s_setprio 1
	s_waitcnt lgkmcnt(0)
	v_mfma_f32_16x16x32_bf16 v[116:119], v[208:211], v[176:179], v[116:119]
	v_mfma_f32_16x16x32_bf16 v[108:111], v[216:219], v[176:179], v[108:111]
	v_mfma_f32_16x16x32_bf16 v[100:103], v[208:211], v[184:187], v[100:103]
	v_mfma_f32_16x16x32_bf16 v[92:95], v[216:219], v[184:187], v[92:95]
	v_mfma_f32_16x16x32_bf16 v[84:87], v[208:211], v[192:195], v[84:87]
	v_mfma_f32_16x16x32_bf16 v[76:79], v[216:219], v[192:195], v[76:79]
	v_mfma_f32_16x16x32_bf16 v[68:71], v[208:211], v[200:203], v[68:71]
	v_mfma_f32_16x16x32_bf16 v[64:67], v[216:219], v[200:203], v[64:67]
	v_mfma_f32_16x16x32_bf16 v[116:119], v[212:215], v[180:183], v[116:119]
	v_mfma_f32_16x16x32_bf16 v[108:111], v[220:223], v[180:183], v[108:111]
	v_mfma_f32_16x16x32_bf16 v[100:103], v[212:215], v[188:191], v[100:103]
	v_mfma_f32_16x16x32_bf16 v[92:95], v[220:223], v[188:191], v[92:95]
	v_mfma_f32_16x16x32_bf16 v[84:87], v[212:215], v[196:199], v[84:87]
	v_mfma_f32_16x16x32_bf16 v[76:79], v[220:223], v[196:199], v[76:79]
	v_mfma_f32_16x16x32_bf16 v[68:71], v[212:215], v[204:207], v[68:71]
	v_mfma_f32_16x16x32_bf16 v[64:67], v[220:223], v[204:207], v[64:67]
	s_setprio 0
	s_mov_b32 m0, s7
	v_lshl_add_u64 v[158:159], v[226:227], 0, s[46:47]
	s_barrier
	ds_read_b128 v[176:179], v165 offset:49152
	ds_read_b128 v[180:183], v165 offset:50176
	ds_read_b128 v[184:187], v165 offset:51200
	ds_read_b128 v[188:191], v165 offset:52224
	ds_read_b128 v[192:195], v165 offset:53248
	ds_read_b128 v[196:199], v165 offset:54272
	ds_read_b128 v[200:203], v165 offset:55296
	ds_read_b128 v[204:207], v165 offset:56320
	global_load_lds_dwordx4 v[158:159], off
	v_lshl_add_u64 v[158:159], v[228:229], 0, s[46:47]
	s_mov_b32 m0, s68
	s_nop 0
	global_load_lds_dwordx4 v[158:159], off
	s_barrier
; __device__ __forceinline__ unsigned cvt_pk_bf16(float lo, float hi) { unsigned r; asm volatile("v_cvt_pk_bf16_f32 %0, %1, %2" : "=v"(r) : "v"(lo), "v"(hi)); return r; }
; #define PG8_STAGE(bufoff, gbase, voff) do { _Pragma("unroll") for (int _i = 0; _i < 2; ++_i) \
;         __builtin_amdgcn_global_load_lds((const unsigned*)((const char*)(gbase) + (voff)[_i]), (LAS unsigned*)(lds + (bufoff) + ldsw + _i * 8192), 16, 0, 0); } while (0)
; #define PG8_WAIT_V(n) asm volatile("s_waitcnt vmcnt(" #n ")" ::: "memory")
; #define PG8_WAIT_L(n) asm volatile("s_waitcnt lgkmcnt(" #n ")" ::: "memory")
; #define PG8_BAR __builtin_amdgcn_s_barrier()
; template <class Epi, class Sched>
; __device__ __forceinline__ void gemm_phase(LAS unsigned char* lds, const Gemm g, const Sched& S, const Epi& E) {
;     ...
;             PG8_BAR; PG8_WAIT_L(0); PG8_MMA(1, 0, At, B0); PG8_BAR; PG8_SCHED;
;             PG8_STAGE(PG8_SB(1, 1), b3 + hstepB, voffB);
;             PG8_WAIT_V(6); PG8_BAR; PG8_MMA(1, 1, At, B1); PG8_BAR;
;         }
;         if constexpr (!Epi::AFTER_DRAIN) E(acc, cur, wr, wc, fr, fq);
;         if (!has_next) break;
;     __device__ __forceinline__ void operator()(const f32x4 (&acc)[2][2][4][2], const Unit& u, int wr, int wc, int fr, int fq) const {
;         const int cl = wc * 32 + 8 * fq;
;         const int row0 = u.pm * BM + wr * 64 + fr, t = u.pn;
;         if (t < 4) run<0>(acc, Z + ZSLAB(2 * t, 0), 128, ZSLAB(1, 0), row0, cl);
;         else if (t < 8) run<1>(acc, Z + ZSLAB(2 * t, 0), 128, ZSLAB(1, 0), row0, cl);
;         else if (t < 16) {
;             bf16_t* zug = Z + ZSLAB(16 + (t - 8), 0) + cl;
; #pragma unroll
;             for (int ai = 0; ai < 2; ++ai)
; #pragma unroll
;                 for (int m = 0; m < 4; ++m) { f32x4 o0, o1;
; #pragma unroll
;                     for (int j = 0; j < 4; ++j) { o0[j] = act_gelu_silu(acc[ai][0][m][0][j], acc[ai][1][m][0][j]); o1[j] = act_gelu_silu(acc[ai][0][m][1][j], acc[ai][1][m][1][j]); }
;                     u32x4 w; w.x = cvt_pk_bf16(o0[0], o0[1]); w.y = cvt_pk_bf16(o0[2], o0[3]); w.z = cvt_pk_bf16(o1[0], o1[1]); w.w = cvt_pk_bf16(o1[2], o1[3]);
;                     *(u32x4*)(zug + (size_t)(row0 + ai * HALF + m * 16) * 128) = w; }
;         }
;         else run<2, true>(acc, Z + ZSLAB(24 + 2 * (t - 16), 0), 128, ZSLAB(1, 0), row0, cl, stats, (t - 16) * 4 + wc, fq);
	s_waitcnt lgkmcnt(0)
	s_setprio 1
	s_waitcnt lgkmcnt(0)
	v_mfma_f32_16x16x32_bf16 v[60:63], v[150:153], v[176:179], v[60:63]
	v_mfma_f32_16x16x32_bf16 v[56:59], v[168:171], v[176:179], v[56:59]
	v_mfma_f32_16x16x32_bf16 v[48:51], v[150:153], v[184:187], v[48:51]
	v_mfma_f32_16x16x32_bf16 v[40:43], v[168:171], v[184:187], v[40:43]
	v_mfma_f32_16x16x32_bf16 v[36:39], v[150:153], v[192:195], v[36:39]
	v_mfma_f32_16x16x32_bf16 v[28:31], v[168:171], v[192:195], v[28:31]
	v_mfma_f32_16x16x32_bf16 v[20:23], v[150:153], v[200:203], v[20:23]
	v_mfma_f32_16x16x32_bf16 v[12:15], v[168:171], v[200:203], v[12:15]
	v_mfma_f32_16x16x32_bf16 v[60:63], v[154:157], v[180:183], v[60:63]
	v_mfma_f32_16x16x32_bf16 v[56:59], v[172:175], v[180:183], v[56:59]
	v_mfma_f32_16x16x32_bf16 v[48:51], v[154:157], v[188:191], v[48:51]
	v_mfma_f32_16x16x32_bf16 v[40:43], v[172:175], v[188:191], v[40:43]
	v_mfma_f32_16x16x32_bf16 v[36:39], v[154:157], v[196:199], v[36:39]
	v_mfma_f32_16x16x32_bf16 v[28:31], v[172:175], v[196:199], v[28:31]
	v_mfma_f32_16x16x32_bf16 v[20:23], v[154:157], v[204:207], v[20:23]
	v_mfma_f32_16x16x32_bf16 v[12:15], v[172:175], v[204:207], v[12:15]
	s_setprio 0
	s_barrier
	s_add_u32 s72, s72, 0x40080
	s_addc_u32 s73, s73, 0
	s_add_i32 s49, s51, s95
	v_lshl_add_u64 v[150:151], s[72:73], 0, v[138:139]
	s_mov_b32 m0, s49
	s_nop 0
	global_load_lds_dwordx4 v[150:151], off
	v_lshl_add_u64 v[150:151], s[72:73], 0, v[134:135]
	s_add_i32 m0, s49, 0x2000
	s_nop 0
	global_load_lds_dwordx4 v[150:151], off
	s_waitcnt vmcnt(6)
	s_barrier
	s_setprio 1
	v_mfma_f32_16x16x32_bf16 v[52:55], v[208:211], v[176:179], v[52:55]
	v_mfma_f32_16x16x32_bf16 v[44:47], v[216:219], v[176:179], v[44:47]
	v_mfma_f32_16x16x32_bf16 v[32:35], v[208:211], v[184:187], v[32:35]
	v_mfma_f32_16x16x32_bf16 v[24:27], v[216:219], v[184:187], v[24:27]
	v_mfma_f32_16x16x32_bf16 v[16:19], v[208:211], v[192:195], v[16:19]
	v_mfma_f32_16x16x32_bf16 v[8:11], v[216:219], v[192:195], v[8:11]
	v_mfma_f32_16x16x32_bf16 v[4:7], v[208:211], v[200:203], v[4:7]
	v_mfma_f32_16x16x32_bf16 v[0:3], v[216:219], v[200:203], v[0:3]
	v_mfma_f32_16x16x32_bf16 v[52:55], v[212:215], v[180:183], v[52:55]
	v_mfma_f32_16x16x32_bf16 v[44:47], v[220:223], v[180:183], v[44:47]
	v_mfma_f32_16x16x32_bf16 v[32:35], v[212:215], v[188:191], v[32:35]
	v_mfma_f32_16x16x32_bf16 v[24:27], v[220:223], v[188:191], v[24:27]
	v_mfma_f32_16x16x32_bf16 v[16:19], v[212:215], v[196:199], v[16:19]
	v_mfma_f32_16x16x32_bf16 v[8:11], v[220:223], v[196:199], v[8:11]
	v_mfma_f32_16x16x32_bf16 v[4:7], v[212:215], v[204:207], v[4:7]
	v_mfma_f32_16x16x32_bf16 v[0:3], v[220:223], v[204:207], v[0:3]
	s_setprio 0
	s_add_i32 s29, s29, 2
	s_add_u32 s70, s70, 0x100
	s_addc_u32 s71, s71, 0
	s_add_u32 s27, s27, 0x100
	s_addc_u32 s28, s28, 0
	s_cmp_gt_u32 s29, 13
	s_barrier
	s_cbranch_scc0 .LBB0_140
	v_lshl_add_u32 v150, s2, 8, v163
	s_cmp_gt_i32 s87, 3
	s_mov_b64 s[70:71], -1
	s_cbranch_scc0 .LBB0_167
	s_cmp_gt_u32 s87, 7
	s_cbranch_scc0 .LBB0_164
	v_mul_f32_e32 v129, v124, v124
	v_mul_f32_e32 v149, v120, v120
	v_mul_f32_e32 v151, v125, v125
	v_mul_f32_e32 v152, v121, v121
	v_mul_f32_e32 v153, v126, v126
	v_mul_f32_e32 v154, v122, v122
	v_mul_f32_e32 v155, v127, v127
	v_mul_f32_e32 v156, v123, v123
	s_cmp_gt_u32 s87, 15
	v_fmamk_f32 v174, v129, 0xbdd2d3e7, v160
	v_fmamk_f32 v173, v149, 0xbdd2d3e7, v160
	v_fmamk_f32 v172, v151, 0xbdd2d3e7, v160
	v_fmamk_f32 v171, v152, 0xbdd2d3e7, v160
	v_fmamk_f32 v170, v153, 0xbdd2d3e7, v160
	v_fmamk_f32 v169, v154, 0xbdd2d3e7, v160
	v_fmamk_f32 v168, v155, 0xbdd2d3e7, v160
	v_fmamk_f32 v166, v156, 0xbdd2d3e7, v160
	s_cbranch_scc0 .LBB0_161
; __device__ __forceinline__ unsigned cvt_pk_bf16(float lo, float hi) { unsigned r; asm volatile("v_cvt_pk_bf16_f32 %0, %1, %2" : "=v"(r) : "v"(lo), "v"(hi)); return r; }
; __device__ __forceinline__ float act_silu(float v) { return v * fast_sigmoid(v); }
; #pragma unroll
;         for (int ai = 0; ai < 2; ++ai)
; #pragma unroll
;             for (int m = 0; m < 4; ++m) { bf16_t* rowp = base + (size_t)(row0 + ai * HALF + m * 16) * ldc + col0; float ps = 0.f, pq = 0.f;
; #pragma unroll
;                 for (int bj = 0; bj < 2; ++bj) { f32x4 v0 = acc[ai][bj][m][0], v1 = acc[ai][bj][m][1];
;                     if (ACT == 1) {
; #pragma unroll
;                         for (int j = 0; j < 4; ++j) { v0[j] = act_silu(v0[j]); v1[j] = act_silu(v1[j]); } }
;                     if (ACT == 2) {
; #pragma unroll
;                         for (int j = 0; j < 4; ++j) { v0[j] = act_gelu_tanh(v0[j]); v1[j] = act_gelu_tanh(v1[j]); } }
;                     if (STATS) {
; #pragma unroll
;                         for (int j = 0; j < 4; ++j) { ps += v0[j] + v1[j]; pq += v0[j] * v0[j] + v1[j] * v1[j]; } }
;                     u32x4 w; w.x = cvt_pk_bf16(v0[0], v0[1]); w.y = cvt_pk_bf16(v0[2], v0[3]); w.z = cvt_pk_bf16(v1[0], v1[1]); w.w = cvt_pk_bf16(v1[2], v1[3]);
;                     *(u32x4*)(rowp + bj * bjstep) = w; }
;                 if (STATS) {
;                     ps += __shfl_xor(ps, 16); ps += __shfl_xor(ps, 32); pq += __shfl_xor(pq, 16); pq += __shfl_xor(pq, 32);
;                     if (fq == 0) { f32x2 o; o[0] = ps; o[1] = pq; *(f32x2*)(st + ((size_t)(row0 + ai * HALF + m * 16) * 16 + slot) * 2) = o; } } }
	s_lshl_b32 s98, s24, 9
	v_add_u32_e32 v240, s98, v167
	v_lshlrev_b32_e32 v241, 5, v240
	v_lshlrev_b32_e32 v242, 4, v240
	s_add_u32 s98, s22, 0x3400000
	s_addc_u32 s99, s23, 0
	s_add_u32 s100, s22, 0x200000
	s_addc_u32 s101, s23, 0
	global_load_dwordx4 v[244:247], v241, s[98:99]
	global_load_dwordx4 v[248:251], v241, s[98:99] offset:16
	global_load_dwordx4 v[236:239], v242, s[100:101]
	v_mul_f32_e32 v129, v124, v174
	s_add_i32 s2, s87, -16
	v_exp_f32_e32 v129, v129
	v_mul_f32_e32 v149, v120, v173
	s_lshl_b32 s11, s2, 1
	v_exp_f32_e32 v149, v149
	s_add_i32 s14, s11, 24
	s_lshl_b64 s[26:27], s[14:15], 22
	v_ashrrev_i32_e32 v151, 31, v150
	v_lshl_add_u64 v[152:153], v[142:143], 0, s[26:27]
	v_lshlrev_b64 v[154:155], 8, v[150:151]
	v_add_f32_e32 v129, 1.0, v129
	v_lshl_add_u64 v[158:159], v[152:153], 0, v[154:155]
	v_rcp_f32_e32 v154, v129
	v_add_f32_e32 v129, 1.0, v149
	v_rcp_f32_e32 v155, v129
	v_mov_b32_e32 v156, v124
	v_mov_b32_e32 v157, v120
	v_mul_f32_e32 v181, v116, v116
	v_pk_mul_f32 v[176:177], v[156:157], v[154:155]
	v_fmamk_f32 v181, v181, 0xbdd2d3e7, v160
	v_mul_f32_e32 v182, v108, v108
	v_mul_f32_e32 v181, v116, v181
	v_fmamk_f32 v182, v182, 0xbdd2d3e7, v160
	v_pk_fma_f32 v[154:155], v[156:157], v[154:155], v[176:177] op_sel:[0,0,1] op_sel_hi:[1,1,0]
	v_mul_f32_e32 v156, v117, v117
	v_exp_f32_e32 v181, v181
	v_mul_f32_e32 v182, v108, v182
	v_fmamk_f32 v156, v156, 0xbdd2d3e7, v160
	v_mul_f32_e32 v157, v109, v109
	v_exp_f32_e32 v182, v182
	v_mul_f32_e32 v156, v117, v156
	v_fmamk_f32 v157, v157, 0xbdd2d3e7, v160
	v_mul_f32_e32 v129, v125, v172
	v_exp_f32_e32 v156, v156
	v_mul_f32_e32 v157, v109, v157
	v_exp_f32_e32 v129, v129
	v_mul_f32_e32 v149, v121, v171
	v_exp_f32_e32 v157, v157
	v_exp_f32_e32 v149, v149
	v_add_f32_e32 v155, 1.0, v181
	v_rcp_f32_e32 v194, v155
	v_add_f32_e32 v155, 1.0, v182
	v_rcp_f32_e32 v195, v155
	v_add_f32_e32 v155, 1.0, v156
	v_mul_f32_e32 v156, v118, v118
	v_add_f32_e32 v129, 1.0, v129
	v_rcp_f32_e32 v196, v155
	v_add_f32_e32 v155, 1.0, v157
	v_fmamk_f32 v156, v156, 0xbdd2d3e7, v160
	v_mul_f32_e32 v157, v110, v110
	v_rcp_f32_e32 v178, v129
	v_add_f32_e32 v129, 1.0, v149
	v_mul_f32_e32 v149, v126, v170
	v_mul_f32_e32 v175, v122, v169
	v_mul_f32_e32 v156, v118, v156
	v_fmamk_f32 v157, v157, 0xbdd2d3e7, v160
	v_exp_f32_e32 v149, v149
	v_exp_f32_e32 v175, v175
	v_mul_f32_e32 v179, v123, v166
	v_exp_f32_e32 v156, v156
	v_mul_f32_e32 v157, v110, v157
	v_exp_f32_e32 v179, v179
	v_exp_f32_e32 v157, v157
	v_rcp_f32_e32 v180, v129
	v_add_f32_e32 v129, 1.0, v149
	v_add_f32_e32 v149, 1.0, v175
	v_mul_f32_e32 v175, v127, v168
	v_rcp_f32_e32 v197, v155
	v_add_f32_e32 v155, 1.0, v156
	v_mul_f32_e32 v156, v119, v119
	v_exp_f32_e32 v175, v175
	v_add_f32_e32 v179, 1.0, v179
	v_rcp_f32_e32 v198, v155
	v_add_f32_e32 v155, 1.0, v157
	v_fmamk_f32 v156, v156, 0xbdd2d3e7, v160
	v_mul_f32_e32 v157, v111, v111
	v_rcp_f32_e32 v179, v179
	v_mul_f32_e32 v156, v119, v156
	v_fmamk_f32 v157, v157, 0xbdd2d3e7, v160
	v_exp_f32_e32 v156, v156
	v_mul_f32_e32 v157, v111, v157
	v_exp_f32_e32 v157, v157
	v_rcp_f32_e32 v129, v129
	v_rcp_f32_e32 v149, v149
	v_add_f32_e32 v175, 1.0, v175
	v_rcp_f32_e32 v175, v175
	v_mul_f32_e32 v186, v123, v179
	v_mov_b32_e32 v188, v125
	v_mov_b32_e32 v189, v176
	v_mov_b32_e32 v179, v176
	v_mov_b32_e32 v192, v121
	v_mov_b32_e32 v193, v177
	v_mov_b32_e32 v181, v177
	v_rcp_f32_e32 v199, v155
	v_add_f32_e32 v155, 1.0, v156
	v_pk_mul_f32 v[190:191], v[188:189], v[178:179]
	v_pk_mul_f32 v[180:181], v[192:193], v[180:181]
	v_rcp_f32_e32 v200, v155
	v_add_f32_e32 v155, 1.0, v157
	v_pk_fma_f32 v[178:179], v[188:189], v[178:179], v[180:181]
	v_pk_mul_f32 v[188:189], v[190:191], v[190:191]
	v_pk_mul_f32 v[192:193], v[180:181], v[180:181]
	v_rcp_f32_e32 v201, v155
	v_mul_f32_e32 v156, v126, v129
	v_mul_f32_e32 v182, v122, v149
	v_mov_b32_e32 v155, v188
	v_mov_b32_e32 v129, v192
	v_mul_f32_e32 v184, v127, v175
	v_pk_add_f32 v[154:155], v[154:155], v[128:129]
	v_mul_f32_e32 v157, v156, v156
	v_mul_f32_e32 v183, v182, v182
	v_pk_add_f32 v[154:155], v[178:179], v[154:155]
	v_pk_add_f32 v[178:179], v[156:157], v[182:183]
	v_mul_f32_e32 v185, v184, v184
	v_mul_f32_e32 v187, v186, v186
	v_pk_add_f32 v[154:155], v[178:179], v[154:155]
	v_pk_add_f32 v[178:179], v[184:185], v[186:187]
	v_and_b32_e32 v149, 64, v162
	v_pk_add_f32 v[178:179], v[178:179], v[154:155]
	v_cvt_pk_bf16_f32 v154, v176, v190
	v_cvt_pk_bf16_f32 v155, v156, v184
	v_cvt_pk_bf16_f32 v156, v177, v180
	v_cvt_pk_bf16_f32 v157, v182, v186
	global_store_dwordx4 v[158:159], v[154:157], off
	v_mul_f32_e32 v176, v117, v196
	v_mul_f32_e32 v180, v109, v197
	v_mul_f32_e32 v154, v116, v194
	v_mul_f32_e32 v156, v108, v195
	v_mul_f32_e32 v155, v154, v154
	v_mul_f32_e32 v157, v156, v156
	v_mul_f32_e32 v182, v118, v198
	v_mul_f32_e32 v184, v110, v199
	v_pk_add_f32 v[190:191], v[154:155], v[156:157]
	v_mul_f32_e32 v177, v176, v176
	v_mul_f32_e32 v181, v180, v180
	v_mul_f32_e32 v186, v119, v200
	v_mul_f32_e32 v188, v111, v201
	v_pk_add_f32 v[178:179], v[178:179], v[190:191]
	v_pk_add_f32 v[190:191], v[176:177], v[180:181]
	v_mul_f32_e32 v183, v182, v182
	v_mul_f32_e32 v185, v184, v184
	v_xor_b32_e32 v129, 16, v162
	v_add_u32_e32 v157, 64, v149
	v_pk_add_f32 v[178:179], v[190:191], v[178:179]
	v_pk_add_f32 v[190:191], v[182:183], v[184:185]
	v_mul_f32_e32 v187, v186, v186
	v_mul_f32_e32 v189, v188, v188
	v_cmp_lt_i32_e32 vcc, v129, v157
	v_pk_add_f32 v[178:179], v[190:191], v[178:179]
	v_pk_add_f32 v[190:191], v[186:187], v[188:189]
	v_cndmask_b32_e32 v129, v162, v129, vcc
	v_pk_add_f32 v[190:191], v[190:191], v[178:179]
	v_lshlrev_b32_e32 v149, 2, v129
	ds_bpermute_b32 v192, v149, v190
	ds_bpermute_b32 v193, v149, v191
	v_xor_b32_e32 v129, 32, v162
	v_cmp_lt_i32_e32 vcc, v129, v157
	v_cvt_pk_bf16_f32 v176, v154, v176
	s_lshl_b32 s2, s2, 3
	s_waitcnt lgkmcnt(0)
	v_pk_add_f32 v[154:155], v[190:191], v[192:193]
	v_cndmask_b32_e32 v129, v162, v129, vcc
	v_lshlrev_b32_e32 v175, 2, v129
	v_cvt_pk_bf16_f32 v177, v182, v186
	v_cvt_pk_bf16_f32 v178, v156, v180
	ds_bpermute_b32 v156, v175, v154
	ds_bpermute_b32 v157, v175, v155
	s_or_b32 s14, s2, s3
	s_lshl_b64 s[26:27], s[14:15], 2
	s_add_u32 s70, s80, s26
	v_add_co_u32_e32 v158, vcc, s88, v158
	s_addc_u32 s71, s81, s27
	s_nop 0
	v_addc_co_u32_e32 v159, vcc, 0, v159, vcc
	v_cvt_pk_bf16_f32 v179, v184, v188
	global_store_dwordx4 v[158:159], v[176:179], off
	s_and_saveexec_b64 s[72:73], s[0:1]
	s_cbranch_execz .LBB0_146
	s_waitcnt lgkmcnt(0)
	v_pk_add_f32 v[154:155], v[154:155], v[156:157]
	v_lshlrev_b64 v[156:157], 7, v[150:151]
	v_lshl_add_u64 v[156:157], s[70:71], 0, v[156:157]
	global_store_dwordx2 v[156:157], v[154:155], off
